# pool phase items rebalanced: second item of each block uses group 3-g (pairs W=16 with W=2 items)
# speedup vs baseline: 1.0073x; 1.0073x over previous
; DI void pool_phase(const bf16_t* proj, bf16_t* cat, const bf16_t* Wp, const float* scale, char* lds) {
;     ...
;   for (int item = blockIdx.x; item < 512; item += gridDim.x) {
;     const int g = item & 3, tt = item >> 2, t0 = tt * 128, tin0 = t0 & (SEQ - 1);
;     if (g == 0) pool_fill<2, 4>(proj, Wp, sD, sW, tid, t0, tin0, g); else if (g == 1) pool_fill<4, 4>(proj, Wp, sD, sW, tid, t0, tin0, g);
;     else if (g == 2) pool_fill<8, 2>(proj, Wp, sD, sW, tid, t0, tin0, g); else pool_fill<16, 1>(proj, Wp, sD, sW, tid, t0, tin0, g);
.LBB0_1146:
	s_lshr_b32 s0, s66, 8
	s_mul_i32 s0, s0, 3
	s_xor_b32 s34, s66, s0
	s_lshl_b32 s0, s34, 5
	s_and_b32 s34, s34, 3
	s_and_b32 s67, s0, 0xffffff80
	s_and_b32 s28, s0, 0x1f80
	s_cmp_lt_i32 s34, 2
	s_mov_b64 s[0:1], -1
	s_cbranch_scc1 .LBB0_1155
	s_cmp_gt_i32 s34, 2
	s_cbranch_scc0 .LBB0_1151
	s_mov_b32 s37, 0
